# k16 + drop ALIGN_EPI/stagger barrier pair at interior unit boundaries of G1 and Wup (epilogue of one half overlaps other half MFMA)
# baseline (speedup 1.0000x reference)
; #define PG8_STAGE(bufoff, gbase, voff) do { _Pragma("unroll") for (int _i = 0; _i < 2; ++_i) \
;         __builtin_amdgcn_global_load_lds((const unsigned*)((const char*)(gbase) + (voff)[_i]), (LAS unsigned*)(lds + (bufoff) + ldsw + _i * 8192), 16, 0, 0); } while (0)
; #define PG8_LDA(dst, b, h) do { _Pragma("unroll") for (int m = 0; m < 4; ++m) _Pragma("unroll") for (int k = 0; k < 2; ++k) dst[m][k] = *(const LAS bf16x8*)(lds + PG8_SA(b, h) + aoff + m * 2048 + k * 1024); } while (0)
; #define PG8_LDB(dst, b, h) do { _Pragma("unroll") for (int n = 0; n < 2; ++n) _Pragma("unroll") for (int k = 0; k < 2; ++k) dst[n][k] = *(const LAS bf16x8*)(lds + PG8_SB(b, h) + boff + n * 2048 + k * 1024); } while (0)
; #define PG8_MMA(ai, bj, At, Bt) do { __builtin_amdgcn_s_setprio(1); _Pragma("unroll") for (int m = 0; m < 4; ++m) _Pragma("unroll") for (int n = 0; n < 2; ++n) _Pragma("unroll") for (int k = 0; k < 2; ++k) \
;         acc[ai][bj][m][n] = __builtin_amdgcn_mfma_f32_16x16x32_bf16(Bt[n][k], At[m][k], acc[ai][bj][m][n], 0, 0, 0); __builtin_amdgcn_s_setprio(0); } while (0)
; #define PG8_WAIT_V(n) asm volatile("s_waitcnt vmcnt(" #n ")" ::: "memory")
; template <class Epi>
; __device__ __forceinline__ void gemm_phase(LAS unsigned char* lds, const int tid, const Gemm g, const StaticOrder& S, const Epi& E) {
;     ...
;             const bool last = (t == nt - 2);
;             const char* a1 = cA + (size_t)(t + 1) * kstep;
;             const char* a2 = last ? nA : cA + (size_t)(t + 2) * kstep; const char* b2 = last ? nB : cB + (size_t)(t + 2) * kstep;
;             const char* a3 = a2 + kstep; const char* b3 = b2 + kstep;
;             PG8_LDB(B0, 0, 0); PG8_LDB(B1, 0, 1); PG8_SCHED; PG8_LDA(At, 0, 0); PG8_STAGE(PG8_SA(1, 1), a1 + hstepA, voffA);
;             PG8_WAIT_V(8); PG8_WAIT_L(0); PG8_BAR; PG8_MMA(0, 0, At, B0); PG8_MMA(0, 1, At, B1); PG8_BAR; PG8_SCHED;
;             PG8_LDA(At, 0, 1); PG8_STAGE(PG8_SB(0, 0), b2, voffB); PG8_STAGE(PG8_SB(0, 1), b2 + hstepB, voffB); PG8_STAGE(PG8_SA(0, 0), a2, voffA);
;             PG8_WAIT_V(8); PG8_WAIT_L(0); PG8_BAR; PG8_MMA(1, 0, At, B0); PG8_MMA(1, 1, At, B1); PG8_BAR; PG8_SCHED;
;             PG8_LDB(B0, 1, 0); PG8_LDB(B1, 1, 1); PG8_SCHED; PG8_LDA(At, 1, 0); PG8_STAGE(PG8_SA(0, 1), a2 + hstepA, voffA);
;             PG8_WAIT_V(8); PG8_WAIT_L(0); PG8_BAR; PG8_MMA(0, 0, At, B0); PG8_MMA(0, 1, At, B1); PG8_BAR; PG8_SCHED;
.LBB0_414:
	s_add_u32 s10, s68, 0xfffc0080
	s_addc_u32 s11, s69, -1
	s_add_i32 s17, 0, 0x10000
	s_cmp_eq_u32 s16, 12
	s_cselect_b32 s73, s7, s11
	s_cselect_b32 s72, s67, s10
	s_cselect_b32 s71, s5, s76
	s_cselect_b32 s70, vcc_lo, vcc_hi
	s_add_i32 s0, 0, 0x14000
	v_add_u32_e32 v70, s17, v202
	v_add_u32_e32 v160, s0, v202
	ds_read_b128 v[50:53], v70
	ds_read_b128 v[54:57], v70 offset:1024
	ds_read_b128 v[66:69], v70 offset:2048
	ds_read_b128 v[70:73], v70 offset:3072
	ds_read_b128 v[156:159], v160
	ds_read_b128 v[170:173], v160 offset:1024
	ds_read_b128 v[174:177], v160 offset:2048
	ds_read_b128 v[178:181], v160 offset:3072
	v_lshl_add_u64 v[160:161], s[68:69], 0, v[152:153]
	s_add_i32 m0, s83, 0xc000
	s_nop 0
	global_load_lds_dwordx4 v[160:161], off
	v_lshl_add_u64 v[160:161], s[68:69], 0, v[154:155]
	s_add_i32 m0, s83, 0xe000
	s_nop 0
	global_load_lds_dwordx4 v[160:161], off
	ds_read_b128 v[216:219], v215
	ds_read_b128 v[220:223], v215 offset:1024
	ds_read_b128 v[224:227], v215 offset:2048
	ds_read_b128 v[228:231], v215 offset:3072
	ds_read_b128 v[232:235], v215 offset:4096
	ds_read_b128 v[236:239], v215 offset:5120
	ds_read_b128 v[240:243], v215 offset:6144
	ds_read_b128 v[244:247], v215 offset:7168
	s_waitcnt vmcnt(8)
	s_waitcnt lgkmcnt(0)
	s_barrier
	s_setprio 1
	s_waitcnt lgkmcnt(0)
	v_mfma_f32_16x16x32_bf16 v[142:145], v[50:53], v[216:219], v[142:145]
	v_mfma_f32_16x16x32_bf16 v[138:141], v[66:69], v[216:219], v[138:141]
	v_mfma_f32_16x16x32_bf16 v[126:129], v[50:53], v[224:227], v[126:129]
	v_mfma_f32_16x16x32_bf16 v[122:125], v[66:69], v[224:227], v[122:125]
	v_mfma_f32_16x16x32_bf16 v[110:113], v[50:53], v[232:235], v[110:113]
	v_mfma_f32_16x16x32_bf16 v[106:109], v[66:69], v[232:235], v[106:109]
	v_mfma_f32_16x16x32_bf16 v[94:97], v[50:53], v[240:243], v[94:97]
	v_mfma_f32_16x16x32_bf16 v[90:93], v[66:69], v[240:243], v[90:93]
	v_mfma_f32_16x16x32_bf16 v[142:145], v[54:57], v[220:223], v[142:145]
	v_mfma_f32_16x16x32_bf16 v[138:141], v[70:73], v[220:223], v[138:141]
	v_mfma_f32_16x16x32_bf16 v[126:129], v[54:57], v[228:231], v[126:129]
	v_mfma_f32_16x16x32_bf16 v[122:125], v[70:73], v[228:231], v[122:125]
	v_mfma_f32_16x16x32_bf16 v[110:113], v[54:57], v[236:239], v[110:113]
	v_mfma_f32_16x16x32_bf16 v[106:109], v[70:73], v[236:239], v[106:109]
	v_mfma_f32_16x16x32_bf16 v[94:97], v[54:57], v[244:247], v[94:97]
	v_mfma_f32_16x16x32_bf16 v[90:93], v[70:73], v[244:247], v[90:93]
	s_setprio 0
	s_setprio 1
	v_mfma_f32_16x16x32_bf16 v[134:137], v[156:159], v[216:219], v[134:137]
	v_mfma_f32_16x16x32_bf16 v[130:133], v[174:177], v[216:219], v[130:133]
	v_mfma_f32_16x16x32_bf16 v[118:121], v[156:159], v[224:227], v[118:121]
	v_mfma_f32_16x16x32_bf16 v[114:117], v[174:177], v[224:227], v[114:117]
	v_mfma_f32_16x16x32_bf16 v[102:105], v[156:159], v[232:235], v[102:105]
	v_mfma_f32_16x16x32_bf16 v[98:101], v[174:177], v[232:235], v[98:101]
	v_mfma_f32_16x16x32_bf16 v[86:89], v[156:159], v[240:243], v[86:89]
	v_mfma_f32_16x16x32_bf16 v[82:85], v[174:177], v[240:243], v[82:85]
	v_mfma_f32_16x16x32_bf16 v[134:137], v[170:173], v[220:223], v[134:137]
	v_mfma_f32_16x16x32_bf16 v[130:133], v[178:181], v[220:223], v[130:133]
	v_mfma_f32_16x16x32_bf16 v[118:121], v[170:173], v[228:231], v[118:121]
	v_mfma_f32_16x16x32_bf16 v[114:117], v[178:181], v[228:231], v[114:117]
	v_mfma_f32_16x16x32_bf16 v[102:105], v[170:173], v[236:239], v[102:105]
	v_mfma_f32_16x16x32_bf16 v[98:101], v[178:181], v[236:239], v[98:101]
	v_mfma_f32_16x16x32_bf16 v[86:89], v[170:173], v[244:247], v[86:89]
	v_mfma_f32_16x16x32_bf16 v[82:85], v[178:181], v[244:247], v[82:85]
	s_setprio 0
	s_barrier
	s_add_i32 s1, s17, s82
	v_lshl_add_u64 v[160:161], s[70:71], 0, v[0:1]
	s_mov_b32 m0, s1
	s_nop 0
	global_load_lds_dwordx4 v[160:161], off
	s_add_i32 m0, s1, 0x2000
	s_add_u32 s10, s70, 0x40000
	v_lshl_add_u64 v[182:183], s[70:71], 0, v[146:147]
	s_addc_u32 s11, s71, 0
	s_add_i32 s0, s0, s82
	global_load_lds_dwordx4 v[182:183], off
	v_lshl_add_u64 v[162:163], s[10:11], 0, v[0:1]
	s_mov_b32 m0, s0
	v_lshl_add_u64 v[164:165], s[72:73], 0, v[150:151]
	global_load_lds_dwordx4 v[162:163], off
	v_lshl_add_u64 v[162:163], s[10:11], 0, v[146:147]
	s_add_i32 m0, s0, 0x2000
	s_nop 0
	global_load_lds_dwordx4 v[162:163], off
	v_lshl_add_u64 v[162:163], s[72:73], 0, v[148:149]
	s_mov_b32 m0, s83
	s_nop 0
	global_load_lds_dwordx4 v[162:163], off
	s_mov_b32 m0, s88
	s_nop 0
	global_load_lds_dwordx4 v[164:165], off
	ds_read_b128 v[216:219], v215 offset:16384
	ds_read_b128 v[220:223], v215 offset:17408
	ds_read_b128 v[224:227], v215 offset:18432
	ds_read_b128 v[228:231], v215 offset:19456
	ds_read_b128 v[232:235], v215 offset:20480
	ds_read_b128 v[236:239], v215 offset:21504
	ds_read_b128 v[240:243], v215 offset:22528
	ds_read_b128 v[244:247], v215 offset:23552
	s_waitcnt vmcnt(8)
	s_waitcnt lgkmcnt(0)
	s_barrier
; #define PG8_STAGE(bufoff, gbase, voff) do { _Pragma("unroll") for (int _i = 0; _i < 2; ++_i) \
;         __builtin_amdgcn_global_load_lds((const unsigned*)((const char*)(gbase) + (voff)[_i]), (LAS unsigned*)(lds + (bufoff) + ldsw + _i * 8192), 16, 0, 0); } while (0)
; #define PG8_LDA(dst, b, h) do { _Pragma("unroll") for (int m = 0; m < 4; ++m) _Pragma("unroll") for (int k = 0; k < 2; ++k) dst[m][k] = *(const LAS bf16x8*)(lds + PG8_SA(b, h) + aoff + m * 2048 + k * 1024); } while (0)
; #define PG8_LDB(dst, b, h) do { _Pragma("unroll") for (int n = 0; n < 2; ++n) _Pragma("unroll") for (int k = 0; k < 2; ++k) dst[n][k] = *(const LAS bf16x8*)(lds + PG8_SB(b, h) + boff + n * 2048 + k * 1024); } while (0)
; #define PG8_MMA(ai, bj, At, Bt) do { __builtin_amdgcn_s_setprio(1); _Pragma("unroll") for (int m = 0; m < 4; ++m) _Pragma("unroll") for (int n = 0; n < 2; ++n) _Pragma("unroll") for (int k = 0; k < 2; ++k) \
;         acc[ai][bj][m][n] = __builtin_amdgcn_mfma_f32_16x16x32_bf16(Bt[n][k], At[m][k], acc[ai][bj][m][n], 0, 0, 0); __builtin_amdgcn_s_setprio(0); } while (0)
; #define PG8_WAIT_V(n) asm volatile("s_waitcnt vmcnt(" #n ")" ::: "memory")
; #define PG8_WAIT_L(n) asm volatile("s_waitcnt lgkmcnt(" #n ")" ::: "memory")
; #define PG8_BAR __builtin_amdgcn_s_barrier()
; #define PG8_SCHED __builtin_amdgcn_sched_barrier(0)
; template <class Epi>
; __device__ __forceinline__ void gemm_phase(LAS unsigned char* lds, const int tid, const Gemm g, const StaticOrder& S, const Epi& E) {
;     ...
;             PG8_WAIT_V(8); PG8_WAIT_L(0); PG8_BAR; PG8_MMA(1, 0, At, B0); PG8_MMA(1, 1, At, B1); PG8_BAR; PG8_SCHED;
;             PG8_LDB(B0, 1, 0); PG8_LDB(B1, 1, 1); PG8_SCHED; PG8_LDA(At, 1, 0); PG8_STAGE(PG8_SA(0, 1), a2 + hstepA, voffA);
;             PG8_WAIT_V(8); PG8_WAIT_L(0); PG8_BAR; PG8_MMA(0, 0, At, B0); PG8_MMA(0, 1, At, B1); PG8_BAR; PG8_SCHED;
;             PG8_LDA(At, 1, 1); PG8_STAGE(PG8_SB(1, 0), b3, voffB); PG8_STAGE(PG8_SB(1, 1), b3 + hstepB, voffB); PG8_STAGE(PG8_SA(1, 0), a3, voffA);
;             PG8_WAIT_V(8); PG8_WAIT_L(0); PG8_BAR; PG8_MMA(1, 0, At, B0); PG8_MMA(1, 1, At, B1); PG8_BAR; PG8_SCHED;
	s_setprio 1
	s_waitcnt lgkmcnt(0)
	v_mfma_f32_16x16x32_bf16 v[78:81], v[50:53], v[216:219], v[78:81]
	v_mfma_f32_16x16x32_bf16 v[74:77], v[66:69], v[216:219], v[74:77]
	v_mfma_f32_16x16x32_bf16 v[46:49], v[50:53], v[224:227], v[46:49]
	v_mfma_f32_16x16x32_bf16 v[42:45], v[66:69], v[224:227], v[42:45]
	v_mfma_f32_16x16x32_bf16 v[30:33], v[50:53], v[232:235], v[30:33]
	v_mfma_f32_16x16x32_bf16 v[26:29], v[66:69], v[232:235], v[26:29]
	v_mfma_f32_16x16x32_bf16 v[14:17], v[50:53], v[240:243], v[14:17]
	v_mfma_f32_16x16x32_bf16 v[10:13], v[66:69], v[240:243], v[10:13]
	v_mfma_f32_16x16x32_bf16 v[78:81], v[54:57], v[220:223], v[78:81]
	v_mfma_f32_16x16x32_bf16 v[74:77], v[70:73], v[220:223], v[74:77]
	v_mfma_f32_16x16x32_bf16 v[46:49], v[54:57], v[228:231], v[46:49]
	v_mfma_f32_16x16x32_bf16 v[42:45], v[70:73], v[228:231], v[42:45]
	v_mfma_f32_16x16x32_bf16 v[30:33], v[54:57], v[236:239], v[30:33]
	v_mfma_f32_16x16x32_bf16 v[26:29], v[70:73], v[236:239], v[26:29]
	v_mfma_f32_16x16x32_bf16 v[14:17], v[54:57], v[244:247], v[14:17]
	v_mfma_f32_16x16x32_bf16 v[10:13], v[70:73], v[244:247], v[10:13]
	s_setprio 0
	s_setprio 1
	v_mfma_f32_16x16x32_bf16 v[38:41], v[156:159], v[224:227], v[38:41]
	v_mfma_f32_16x16x32_bf16 v[34:37], v[174:177], v[224:227], v[34:37]
	v_mfma_f32_16x16x32_bf16 v[22:25], v[156:159], v[232:235], v[22:25]
	v_mfma_f32_16x16x32_bf16 v[18:21], v[174:177], v[232:235], v[18:21]
	v_mfma_f32_16x16x32_bf16 v[6:9], v[156:159], v[240:243], v[6:9]
	v_mfma_f32_16x16x32_bf16 v[2:5], v[174:177], v[240:243], v[2:5]
	v_mfma_f32_16x16x32_bf16 v[50:53], v[156:159], v[216:219], v[62:65]
	v_mfma_f32_16x16x32_bf16 v[54:57], v[174:177], v[216:219], v[58:61]
	v_mfma_f32_16x16x32_bf16 v[38:41], v[170:173], v[228:231], v[38:41]
	v_mfma_f32_16x16x32_bf16 v[34:37], v[178:181], v[228:231], v[34:37]
	v_mfma_f32_16x16x32_bf16 v[22:25], v[170:173], v[236:239], v[22:25]
	v_mfma_f32_16x16x32_bf16 v[18:21], v[178:181], v[236:239], v[18:21]
	v_mfma_f32_16x16x32_bf16 v[6:9], v[170:173], v[244:247], v[6:9]
	v_mfma_f32_16x16x32_bf16 v[2:5], v[178:181], v[244:247], v[2:5]
	v_mfma_f32_16x16x32_bf16 v[50:53], v[170:173], v[220:223], v[50:53]
	v_mfma_f32_16x16x32_bf16 v[54:57], v[178:181], v[220:223], v[54:57]
	s_setprio 0
	s_barrier
	s_add_i32 s0, 0, 0x18000
	s_add_i32 s1, 0, 0x1c000
	v_add_u32_e32 v70, s0, v202
	v_add_u32_e32 v178, s1, v202
	ds_read_b128 v[58:61], v70
	ds_read_b128 v[62:65], v70 offset:1024
	ds_read_b128 v[66:69], v70 offset:2048
	ds_read_b128 v[70:73], v70 offset:3072
	ds_read_b128 v[156:159], v178
	ds_read_b128 v[170:173], v178 offset:1024
	ds_read_b128 v[174:177], v178 offset:2048
	ds_read_b128 v[178:181], v178 offset:3072
	s_add_u32 s10, s72, 0x40000
	s_addc_u32 s11, s73, 0
	s_mov_b32 m0, s89
	v_lshl_add_u64 v[206:207], s[10:11], 0, v[148:149]
	global_load_lds_dwordx4 v[206:207], off
	v_lshl_add_u64 v[206:207], s[10:11], 0, v[150:151]
	s_mov_b32 m0, s92
	s_nop 0
	global_load_lds_dwordx4 v[206:207], off
	ds_read_b128 v[216:219], v215 offset:32768
	ds_read_b128 v[220:223], v215 offset:33792
	ds_read_b128 v[224:227], v215 offset:34816
	ds_read_b128 v[228:231], v215 offset:35840
	ds_read_b128 v[232:235], v215 offset:36864
	ds_read_b128 v[236:239], v215 offset:37888
	ds_read_b128 v[240:243], v215 offset:38912
	ds_read_b128 v[244:247], v215 offset:39936
	s_waitcnt vmcnt(8)
	s_waitcnt lgkmcnt(0)
	s_barrier
	s_setprio 1
	s_waitcnt lgkmcnt(0)
	v_mfma_f32_16x16x32_bf16 v[142:145], v[58:61], v[216:219], v[142:145]
	v_mfma_f32_16x16x32_bf16 v[138:141], v[66:69], v[216:219], v[138:141]
	v_mfma_f32_16x16x32_bf16 v[126:129], v[58:61], v[224:227], v[126:129]
	v_mfma_f32_16x16x32_bf16 v[122:125], v[66:69], v[224:227], v[122:125]
	v_mfma_f32_16x16x32_bf16 v[110:113], v[58:61], v[232:235], v[110:113]
	v_mfma_f32_16x16x32_bf16 v[106:109], v[66:69], v[232:235], v[106:109]
	v_mfma_f32_16x16x32_bf16 v[94:97], v[58:61], v[240:243], v[94:97]
	v_mfma_f32_16x16x32_bf16 v[90:93], v[66:69], v[240:243], v[90:93]
	v_mfma_f32_16x16x32_bf16 v[142:145], v[62:65], v[220:223], v[142:145]
	v_mfma_f32_16x16x32_bf16 v[138:141], v[70:73], v[220:223], v[138:141]
	v_mfma_f32_16x16x32_bf16 v[126:129], v[62:65], v[228:231], v[126:129]
	v_mfma_f32_16x16x32_bf16 v[122:125], v[70:73], v[228:231], v[122:125]
	v_mfma_f32_16x16x32_bf16 v[110:113], v[62:65], v[236:239], v[110:113]
	v_mfma_f32_16x16x32_bf16 v[106:109], v[70:73], v[236:239], v[106:109]
	v_mfma_f32_16x16x32_bf16 v[94:97], v[62:65], v[244:247], v[94:97]
	v_mfma_f32_16x16x32_bf16 v[90:93], v[70:73], v[244:247], v[90:93]
	s_setprio 0
	s_setprio 1
	v_mfma_f32_16x16x32_bf16 v[134:137], v[156:159], v[216:219], v[134:137]
	v_mfma_f32_16x16x32_bf16 v[130:133], v[174:177], v[216:219], v[130:133]
	v_mfma_f32_16x16x32_bf16 v[118:121], v[156:159], v[224:227], v[118:121]
	v_mfma_f32_16x16x32_bf16 v[114:117], v[174:177], v[224:227], v[114:117]
	v_mfma_f32_16x16x32_bf16 v[102:105], v[156:159], v[232:235], v[102:105]
	v_mfma_f32_16x16x32_bf16 v[98:101], v[174:177], v[232:235], v[98:101]
	v_mfma_f32_16x16x32_bf16 v[86:89], v[156:159], v[240:243], v[86:89]
	v_mfma_f32_16x16x32_bf16 v[82:85], v[174:177], v[240:243], v[82:85]
	v_mfma_f32_16x16x32_bf16 v[134:137], v[170:173], v[220:223], v[134:137]
	v_mfma_f32_16x16x32_bf16 v[130:133], v[178:181], v[220:223], v[130:133]
	v_mfma_f32_16x16x32_bf16 v[118:121], v[170:173], v[228:231], v[118:121]
	v_mfma_f32_16x16x32_bf16 v[114:117], v[178:181], v[228:231], v[114:117]
	v_mfma_f32_16x16x32_bf16 v[102:105], v[170:173], v[236:239], v[102:105]
	v_mfma_f32_16x16x32_bf16 v[98:101], v[178:181], v[236:239], v[98:101]
	v_mfma_f32_16x16x32_bf16 v[86:89], v[170:173], v[244:247], v[86:89]
	v_mfma_f32_16x16x32_bf16 v[82:85], v[178:181], v[244:247], v[82:85]
	s_setprio 0
	s_barrier
; #define PG8_STAGE(bufoff, gbase, voff) do { _Pragma("unroll") for (int _i = 0; _i < 2; ++_i) \
;         __builtin_amdgcn_global_load_lds((const unsigned*)((const char*)(gbase) + (voff)[_i]), (LAS unsigned*)(lds + (bufoff) + ldsw + _i * 8192), 16, 0, 0); } while (0)
; #define PG8_LDA(dst, b, h) do { _Pragma("unroll") for (int m = 0; m < 4; ++m) _Pragma("unroll") for (int k = 0; k < 2; ++k) dst[m][k] = *(const LAS bf16x8*)(lds + PG8_SA(b, h) + aoff + m * 2048 + k * 1024); } while (0)
; #define PG8_MMA(ai, bj, At, Bt) do { __builtin_amdgcn_s_setprio(1); _Pragma("unroll") for (int m = 0; m < 4; ++m) _Pragma("unroll") for (int n = 0; n < 2; ++n) _Pragma("unroll") for (int k = 0; k < 2; ++k) \
;         acc[ai][bj][m][n] = __builtin_amdgcn_mfma_f32_16x16x32_bf16(Bt[n][k], At[m][k], acc[ai][bj][m][n], 0, 0, 0); __builtin_amdgcn_s_setprio(0); } while (0)
; #define PG8_WAIT_V(n) asm volatile("s_waitcnt vmcnt(" #n ")" ::: "memory")
; #define PG8_WAIT_L(n) asm volatile("s_waitcnt lgkmcnt(" #n ")" ::: "memory")
; #define PG8_BAR __builtin_amdgcn_s_barrier()
; #define PG8_SCHED __builtin_amdgcn_sched_barrier(0)
; template <class Epi>
; __device__ __forceinline__ void gemm_phase(LAS unsigned char* lds, const int tid, const Gemm g, const StaticOrder& S, const Epi& E) {
;     ...
;             PG8_LDA(At, 1, 1); PG8_STAGE(PG8_SB(1, 0), b3, voffB); PG8_STAGE(PG8_SB(1, 1), b3 + hstepB, voffB); PG8_STAGE(PG8_SA(1, 0), a3, voffA);
;             PG8_WAIT_V(8); PG8_WAIT_L(0); PG8_BAR; PG8_MMA(1, 0, At, B0); PG8_MMA(1, 1, At, B1); PG8_BAR; PG8_SCHED;
;         }
;         if (wr == 0) PG8_BAR;
	s_add_i32 s0, s0, s82
	v_lshl_add_u64 v[160:161], v[160:161], 0, s[36:37]
	s_mov_b32 m0, s0
	s_nop 0
	global_load_lds_dwordx4 v[160:161], off
	s_add_i32 m0, s0, 0x2000
	s_add_u32 s10, s70, 0x40080
	v_lshl_add_u64 v[160:161], v[182:183], 0, s[36:37]
	s_addc_u32 s11, s71, 0
	s_add_i32 s0, s1, s82
	global_load_lds_dwordx4 v[160:161], off
	v_lshl_add_u64 v[160:161], s[10:11], 0, v[0:1]
	s_mov_b32 m0, s0
	s_nop 0
	global_load_lds_dwordx4 v[160:161], off
	v_lshl_add_u64 v[160:161], s[10:11], 0, v[146:147]
	s_add_i32 m0, s0, 0x2000
	s_nop 0
	global_load_lds_dwordx4 v[160:161], off
	v_lshl_add_u64 v[160:161], v[162:163], 0, s[36:37]
	s_mov_b32 m0, s93
	s_nop 0
	global_load_lds_dwordx4 v[160:161], off
	v_lshl_add_u64 v[160:161], v[164:165], 0, s[36:37]
	s_mov_b32 m0, s74
	s_nop 0
	global_load_lds_dwordx4 v[160:161], off
	ds_read_b128 v[216:219], v215 offset:49152
	ds_read_b128 v[220:223], v215 offset:50176
	ds_read_b128 v[224:227], v215 offset:51200
	ds_read_b128 v[228:231], v215 offset:52224
	ds_read_b128 v[232:235], v215 offset:53248
	ds_read_b128 v[236:239], v215 offset:54272
	ds_read_b128 v[240:243], v215 offset:55296
	ds_read_b128 v[244:247], v215 offset:56320
	s_waitcnt vmcnt(8)
	s_waitcnt lgkmcnt(0)
	s_barrier
	s_setprio 1
	s_waitcnt lgkmcnt(0)
	v_mfma_f32_16x16x32_bf16 v[78:81], v[58:61], v[216:219], v[78:81]
	v_mfma_f32_16x16x32_bf16 v[74:77], v[66:69], v[216:219], v[74:77]
	v_mfma_f32_16x16x32_bf16 v[46:49], v[58:61], v[224:227], v[46:49]
	v_mfma_f32_16x16x32_bf16 v[42:45], v[66:69], v[224:227], v[42:45]
	v_mfma_f32_16x16x32_bf16 v[30:33], v[58:61], v[232:235], v[30:33]
	v_mfma_f32_16x16x32_bf16 v[26:29], v[66:69], v[232:235], v[26:29]
	v_mfma_f32_16x16x32_bf16 v[14:17], v[58:61], v[240:243], v[14:17]
	v_mfma_f32_16x16x32_bf16 v[10:13], v[66:69], v[240:243], v[10:13]
	v_mfma_f32_16x16x32_bf16 v[78:81], v[62:65], v[220:223], v[78:81]
	v_mfma_f32_16x16x32_bf16 v[74:77], v[70:73], v[220:223], v[74:77]
	v_mfma_f32_16x16x32_bf16 v[46:49], v[62:65], v[228:231], v[46:49]
	v_mfma_f32_16x16x32_bf16 v[42:45], v[70:73], v[228:231], v[42:45]
	v_mfma_f32_16x16x32_bf16 v[30:33], v[62:65], v[236:239], v[30:33]
	v_mfma_f32_16x16x32_bf16 v[26:29], v[70:73], v[236:239], v[26:29]
	v_mfma_f32_16x16x32_bf16 v[14:17], v[62:65], v[244:247], v[14:17]
	v_mfma_f32_16x16x32_bf16 v[10:13], v[70:73], v[244:247], v[10:13]
	s_setprio 0
	s_setprio 1
	v_mfma_f32_16x16x32_bf16 v[50:53], v[156:159], v[216:219], v[50:53]
	v_mfma_f32_16x16x32_bf16 v[62:65], v[170:173], v[220:223], v[50:53]
	v_mfma_f32_16x16x32_bf16 v[50:53], v[174:177], v[216:219], v[54:57]
	v_mfma_f32_16x16x32_bf16 v[38:41], v[156:159], v[224:227], v[38:41]
	v_mfma_f32_16x16x32_bf16 v[34:37], v[174:177], v[224:227], v[34:37]
	v_mfma_f32_16x16x32_bf16 v[22:25], v[156:159], v[232:235], v[22:25]
	v_mfma_f32_16x16x32_bf16 v[18:21], v[174:177], v[232:235], v[18:21]
	v_mfma_f32_16x16x32_bf16 v[6:9], v[156:159], v[240:243], v[6:9]
	v_mfma_f32_16x16x32_bf16 v[2:5], v[174:177], v[240:243], v[2:5]
	v_mfma_f32_16x16x32_bf16 v[58:61], v[178:181], v[220:223], v[50:53]
	v_mfma_f32_16x16x32_bf16 v[38:41], v[170:173], v[228:231], v[38:41]
	v_mfma_f32_16x16x32_bf16 v[34:37], v[178:181], v[228:231], v[34:37]
	v_mfma_f32_16x16x32_bf16 v[22:25], v[170:173], v[236:239], v[22:25]
	v_mfma_f32_16x16x32_bf16 v[18:21], v[178:181], v[236:239], v[18:21]
	v_mfma_f32_16x16x32_bf16 v[6:9], v[170:173], v[244:247], v[6:9]
	v_mfma_f32_16x16x32_bf16 v[2:5], v[178:181], v[244:247], v[2:5]
	s_setprio 0
	s_barrier
	s_add_i32 s16, s16, 2
	s_add_u32 s68, s68, 0x100
	s_addc_u32 s69, s69, 0
	s_add_u32 vcc_hi, vcc_hi, 0x100
	s_addc_u32 s76, s76, 0
	s_cmp_gt_u32 s16, 13
	s_cbranch_scc0 .LBB0_414
	s_and_b64 vcc, exec, s[2:3]
	s_cbranch_vccz .LBB0_417
	s_and_b64 vcc, exec, s[62:63]
	s_cbranch_vccnz .LBB0_417
	s_barrier

; __device__ __forceinline__ unsigned pk2(float lo, float hi) { const f32x2 v = {lo, hi}; const bf16x2_t b = __builtin_convertvector(v, bf16x2_t); return __builtin_bit_cast(unsigned, b); }
; #define PG8_BAR __builtin_amdgcn_s_barrier()
; template <class Epi>
; __device__ __forceinline__ void gemm_phase(LAS unsigned char* lds, const int tid, const Gemm g, const StaticOrder& S, const Epi& E) {
;     ...
;         if (!has_next) break;
; #pragma unroll
;         for (int a = 0; a < 2; ++a)
; #pragma unroll
;             for (int b = 0; b < 2; ++b)
; #pragma unroll
;                 for (int m = 0; m < 4; ++m)
; #pragma unroll
;                     for (int n = 0; n < 2; ++n) acc[a][b][m][n] = (f32x4){0.f, 0.f, 0.f, 0.f};
;         cur = nxt; cA = nA; cB = nB; ++ui;
;         if (wr == 1) PG8_BAR;
;     template <int NA, int NM> __device__ __forceinline__ void operator()(const f32x4 (&acc)[NA][2][NM][2], const pg8::Unit& u, int ro, int wr, int wc, int fr, int fq) const {
;     ...
;                         w.x = pk2(v0.x, v0.y); w.y = pk2(v0.z, v0.w); w.z = pk2(v1.x, v1.y); w.w = pk2(v1.z, v1.w);
;                         bf16_t* dst = QV + (size_t)row * 2048 + (type == 0 ? c : 1024 + (c - 3072));
;                         *(u32x4*)dst = w;
.LBB0_481:
	v_ashrrev_i32_e32 v135, 31, v134
	v_lshl_add_u64 v[6:7], v[134:135], 1, v[16:17]
	s_andn2_b64 vcc, exec, s[62:63]
	s_mov_b64 s[62:63], -1
	global_store_dwordx4 v[6:7], v[2:5], off
	s_cbranch_vccnz .LBB0_406
	v_readlane_b32 s0, v255, 29
	v_readlane_b32 s1, v255, 30
	s_andn2_b64 vcc, exec, s[0:1]
	s_cbranch_vccnz .LBB0_405
	s_branch .LBB0_405

; #define PG8_STAGE(bufoff, gbase, voff) do { _Pragma("unroll") for (int _i = 0; _i < 2; ++_i) \
;         __builtin_amdgcn_global_load_lds((const unsigned*)((const char*)(gbase) + (voff)[_i]), (LAS unsigned*)(lds + (bufoff) + ldsw + _i * 8192), 16, 0, 0); } while (0)
; #define PG8_LDA(dst, b, h) do { _Pragma("unroll") for (int m = 0; m < 4; ++m) _Pragma("unroll") for (int k = 0; k < 2; ++k) dst[m][k] = *(const LAS bf16x8*)(lds + PG8_SA(b, h) + aoff + m * 2048 + k * 1024); } while (0)
; #define PG8_LDB(dst, b, h) do { _Pragma("unroll") for (int n = 0; n < 2; ++n) _Pragma("unroll") for (int k = 0; k < 2; ++k) dst[n][k] = *(const LAS bf16x8*)(lds + PG8_SB(b, h) + boff + n * 2048 + k * 1024); } while (0)
; #define PG8_MMA(ai, bj, At, Bt) do { __builtin_amdgcn_s_setprio(1); _Pragma("unroll") for (int m = 0; m < 4; ++m) _Pragma("unroll") for (int n = 0; n < 2; ++n) _Pragma("unroll") for (int k = 0; k < 2; ++k) \
;         acc[ai][bj][m][n] = __builtin_amdgcn_mfma_f32_16x16x32_bf16(Bt[n][k], At[m][k], acc[ai][bj][m][n], 0, 0, 0); __builtin_amdgcn_s_setprio(0); } while (0)
; #define PG8_WAIT_V(n) asm volatile("s_waitcnt vmcnt(" #n ")" ::: "memory")
; #define PG8_WAIT_L(n) asm volatile("s_waitcnt lgkmcnt(" #n ")" ::: "memory")
; #define PG8_BAR __builtin_amdgcn_s_barrier()
; #define PG8_SCHED __builtin_amdgcn_sched_barrier(0)
; template <class Epi>
; __device__ __forceinline__ void gemm_phase(LAS unsigned char* lds, const int tid, const Gemm g, const StaticOrder& S, const Epi& E) {
;     ...
;         for (int t = 0; t < nt; t += 2) {
;             const bool last = (t == nt - 2);
;             const char* a1 = cA + (size_t)(t + 1) * kstep;
;             const char* a2 = last ? nA : cA + (size_t)(t + 2) * kstep; const char* b2 = last ? nB : cB + (size_t)(t + 2) * kstep;
;             const char* a3 = a2 + kstep; const char* b3 = b2 + kstep;
;             PG8_LDB(B0, 0, 0); PG8_LDB(B1, 0, 1); PG8_SCHED; PG8_LDA(At, 0, 0); PG8_STAGE(PG8_SA(1, 1), a1 + hstepA, voffA);
;             PG8_WAIT_V(8); PG8_WAIT_L(0); PG8_BAR; PG8_MMA(0, 0, At, B0); PG8_MMA(0, 1, At, B1); PG8_BAR; PG8_SCHED;
;             PG8_LDA(At, 0, 1); PG8_STAGE(PG8_SB(0, 0), b2, voffB); PG8_STAGE(PG8_SB(0, 1), b2 + hstepB, voffB); PG8_STAGE(PG8_SA(0, 0), a2, voffA);
;             PG8_WAIT_V(8); PG8_WAIT_L(0); PG8_BAR; PG8_MMA(1, 0, At, B0); PG8_MMA(1, 1, At, B1); PG8_BAR; PG8_SCHED;
.LBB0_1912:
	s_add_u32 s30, s82, 0xfffc0080
	s_addc_u32 s31, s83, -1
	s_add_i32 s92, 0, 0x10000
	s_cmp_eq_u32 s17, 12
	s_cselect_b32 s89, s7, s31
	s_cselect_b32 s88, s65, s30
	s_cselect_b32 s31, s5, s27
	s_cselect_b32 s30, vcc_lo, vcc_hi
	s_add_i32 s11, 0, 0x14000
	v_add_u32_e32 v110, s92, v158
	v_add_u32_e32 v162, s11, v158
	ds_read_b128 v[98:101], v110
	ds_read_b128 v[102:105], v110 offset:1024
	ds_read_b128 v[106:109], v110 offset:2048
	ds_read_b128 v[110:113], v110 offset:3072
	ds_read_b128 v[174:177], v162
	ds_read_b128 v[178:181], v162 offset:1024
	ds_read_b128 v[182:185], v162 offset:2048
	ds_read_b128 v[186:189], v162 offset:3072
	v_lshl_add_u64 v[162:163], s[82:83], 0, v[152:153]
	s_add_i32 m0, s66, 0xc000
	s_nop 0
	global_load_lds_dwordx4 v[162:163], off
	v_lshl_add_u64 v[162:163], s[82:83], 0, v[154:155]
	s_add_i32 m0, s66, 0xe000
	s_nop 0
	global_load_lds_dwordx4 v[162:163], off
	ds_read_b128 v[190:193], v172
	ds_read_b128 v[194:197], v172 offset:1024
	ds_read_b128 v[198:201], v172 offset:2048
	ds_read_b128 v[210:213], v172 offset:3072
	ds_read_b128 v[214:217], v172 offset:4096
	ds_read_b128 v[218:221], v172 offset:5120
	ds_read_b128 v[222:225], v172 offset:6144
	ds_read_b128 v[226:229], v172 offset:7168
	s_waitcnt vmcnt(8)
	s_waitcnt lgkmcnt(0)
	s_barrier
	s_setprio 1
	s_waitcnt lgkmcnt(0)
	v_mfma_f32_16x16x32_bf16 v[142:145], v[98:101], v[190:193], v[142:145]
	v_mfma_f32_16x16x32_bf16 v[138:141], v[106:109], v[190:193], v[138:141]
	v_mfma_f32_16x16x32_bf16 v[134:137], v[98:101], v[198:201], v[134:137]
	v_mfma_f32_16x16x32_bf16 v[130:133], v[106:109], v[198:201], v[130:133]
	v_mfma_f32_16x16x32_bf16 v[94:97], v[98:101], v[214:217], v[94:97]
	v_mfma_f32_16x16x32_bf16 v[90:93], v[106:109], v[214:217], v[90:93]
	v_mfma_f32_16x16x32_bf16 v[78:81], v[98:101], v[222:225], v[78:81]
	v_mfma_f32_16x16x32_bf16 v[74:77], v[106:109], v[222:225], v[74:77]
	v_mfma_f32_16x16x32_bf16 v[142:145], v[102:105], v[194:197], v[142:145]
	v_mfma_f32_16x16x32_bf16 v[138:141], v[110:113], v[194:197], v[138:141]
	v_mfma_f32_16x16x32_bf16 v[134:137], v[102:105], v[210:213], v[134:137]
	v_mfma_f32_16x16x32_bf16 v[130:133], v[110:113], v[210:213], v[130:133]
	v_mfma_f32_16x16x32_bf16 v[94:97], v[102:105], v[218:221], v[94:97]
	v_mfma_f32_16x16x32_bf16 v[90:93], v[110:113], v[218:221], v[90:93]
	v_mfma_f32_16x16x32_bf16 v[78:81], v[102:105], v[226:229], v[78:81]
	v_mfma_f32_16x16x32_bf16 v[74:77], v[110:113], v[226:229], v[74:77]
	s_setprio 0
	s_setprio 1
	v_mfma_f32_16x16x32_bf16 v[126:129], v[174:177], v[190:193], v[126:129]
	v_mfma_f32_16x16x32_bf16 v[122:125], v[182:185], v[190:193], v[122:125]
	v_mfma_f32_16x16x32_bf16 v[118:121], v[174:177], v[198:201], v[118:121]
	v_mfma_f32_16x16x32_bf16 v[114:117], v[182:185], v[198:201], v[114:117]
	v_mfma_f32_16x16x32_bf16 v[86:89], v[174:177], v[214:217], v[86:89]
	v_mfma_f32_16x16x32_bf16 v[82:85], v[182:185], v[214:217], v[82:85]
	v_mfma_f32_16x16x32_bf16 v[70:73], v[174:177], v[222:225], v[70:73]
	v_mfma_f32_16x16x32_bf16 v[66:69], v[182:185], v[222:225], v[66:69]
	v_mfma_f32_16x16x32_bf16 v[126:129], v[178:181], v[194:197], v[126:129]
	v_mfma_f32_16x16x32_bf16 v[122:125], v[186:189], v[194:197], v[122:125]
	v_mfma_f32_16x16x32_bf16 v[118:121], v[178:181], v[210:213], v[118:121]
	v_mfma_f32_16x16x32_bf16 v[114:117], v[186:189], v[210:213], v[114:117]
	v_mfma_f32_16x16x32_bf16 v[86:89], v[178:181], v[218:221], v[86:89]
	v_mfma_f32_16x16x32_bf16 v[82:85], v[186:189], v[218:221], v[82:85]
	v_mfma_f32_16x16x32_bf16 v[70:73], v[178:181], v[226:229], v[70:73]
	v_mfma_f32_16x16x32_bf16 v[66:69], v[186:189], v[226:229], v[66:69]
	s_setprio 0
	s_barrier
	s_add_i32 s92, s92, s28
	v_lshl_add_u64 v[162:163], s[30:31], 0, v[0:1]
	s_mov_b32 m0, s92
	s_nop 0
	global_load_lds_dwordx4 v[162:163], off
	s_add_i32 m0, s92, 0x2000
	s_add_u32 s92, s30, 0x40000
	v_lshl_add_u64 v[164:165], s[30:31], 0, v[146:147]
	s_addc_u32 s93, s31, 0
	s_add_i32 s11, s11, s28
	global_load_lds_dwordx4 v[164:165], off
	v_lshl_add_u64 v[202:203], s[92:93], 0, v[0:1]
	s_mov_b32 m0, s11
	v_lshl_add_u64 v[206:207], s[88:89], 0, v[148:149]
	global_load_lds_dwordx4 v[202:203], off
	v_lshl_add_u64 v[202:203], s[92:93], 0, v[146:147]
	s_add_i32 m0, s11, 0x2000
	s_nop 0
	global_load_lds_dwordx4 v[202:203], off
	v_lshl_add_u64 v[202:203], s[88:89], 0, v[150:151]
	s_mov_b32 m0, s66
	s_nop 0
	global_load_lds_dwordx4 v[202:203], off
	s_mov_b32 m0, s67
	s_nop 0
	global_load_lds_dwordx4 v[206:207], off
	ds_read_b128 v[190:193], v172 offset:16384
	ds_read_b128 v[194:197], v172 offset:17408
	ds_read_b128 v[198:201], v172 offset:18432
	ds_read_b128 v[210:213], v172 offset:19456
	ds_read_b128 v[214:217], v172 offset:20480
	ds_read_b128 v[218:221], v172 offset:21504
	ds_read_b128 v[222:225], v172 offset:22528
	ds_read_b128 v[226:229], v172 offset:23552
	s_waitcnt vmcnt(8)
	s_waitcnt lgkmcnt(0)
	s_barrier
; #define PG8_STAGE(bufoff, gbase, voff) do { _Pragma("unroll") for (int _i = 0; _i < 2; ++_i) \
;         __builtin_amdgcn_global_load_lds((const unsigned*)((const char*)(gbase) + (voff)[_i]), (LAS unsigned*)(lds + (bufoff) + ldsw + _i * 8192), 16, 0, 0); } while (0)
; #define PG8_LDA(dst, b, h) do { _Pragma("unroll") for (int m = 0; m < 4; ++m) _Pragma("unroll") for (int k = 0; k < 2; ++k) dst[m][k] = *(const LAS bf16x8*)(lds + PG8_SA(b, h) + aoff + m * 2048 + k * 1024); } while (0)
; #define PG8_LDB(dst, b, h) do { _Pragma("unroll") for (int n = 0; n < 2; ++n) _Pragma("unroll") for (int k = 0; k < 2; ++k) dst[n][k] = *(const LAS bf16x8*)(lds + PG8_SB(b, h) + boff + n * 2048 + k * 1024); } while (0)
; #define PG8_MMA(ai, bj, At, Bt) do { __builtin_amdgcn_s_setprio(1); _Pragma("unroll") for (int m = 0; m < 4; ++m) _Pragma("unroll") for (int n = 0; n < 2; ++n) _Pragma("unroll") for (int k = 0; k < 2; ++k) \
;         acc[ai][bj][m][n] = __builtin_amdgcn_mfma_f32_16x16x32_bf16(Bt[n][k], At[m][k], acc[ai][bj][m][n], 0, 0, 0); __builtin_amdgcn_s_setprio(0); } while (0)
; #define PG8_WAIT_V(n) asm volatile("s_waitcnt vmcnt(" #n ")" ::: "memory")
; #define PG8_WAIT_L(n) asm volatile("s_waitcnt lgkmcnt(" #n ")" ::: "memory")
; #define PG8_BAR __builtin_amdgcn_s_barrier()
; #define PG8_SCHED __builtin_amdgcn_sched_barrier(0)
; template <class Epi>
; __device__ __forceinline__ void gemm_phase(LAS unsigned char* lds, const int tid, const Gemm g, const StaticOrder& S, const Epi& E) {
;     ...
;             PG8_WAIT_V(8); PG8_WAIT_L(0); PG8_BAR; PG8_MMA(1, 0, At, B0); PG8_MMA(1, 1, At, B1); PG8_BAR; PG8_SCHED;
;             PG8_LDB(B0, 1, 0); PG8_LDB(B1, 1, 1); PG8_SCHED; PG8_LDA(At, 1, 0); PG8_STAGE(PG8_SA(0, 1), a2 + hstepA, voffA);
;             PG8_WAIT_V(8); PG8_WAIT_L(0); PG8_BAR; PG8_MMA(0, 0, At, B0); PG8_MMA(0, 1, At, B1); PG8_BAR; PG8_SCHED;
	s_setprio 1
	s_waitcnt lgkmcnt(0)
	v_mfma_f32_16x16x32_bf16 v[62:65], v[98:101], v[190:193], v[62:65]
	v_mfma_f32_16x16x32_bf16 v[58:61], v[106:109], v[190:193], v[58:61]
	v_mfma_f32_16x16x32_bf16 v[54:57], v[98:101], v[198:201], v[54:57]
	v_mfma_f32_16x16x32_bf16 v[46:49], v[106:109], v[198:201], v[46:49]
	v_mfma_f32_16x16x32_bf16 v[30:33], v[98:101], v[214:217], v[30:33]
	v_mfma_f32_16x16x32_bf16 v[26:29], v[106:109], v[214:217], v[26:29]
	v_mfma_f32_16x16x32_bf16 v[22:25], v[98:101], v[222:225], v[22:25]
	v_mfma_f32_16x16x32_bf16 v[14:17], v[106:109], v[222:225], v[14:17]
	v_mfma_f32_16x16x32_bf16 v[62:65], v[102:105], v[194:197], v[62:65]
	v_mfma_f32_16x16x32_bf16 v[58:61], v[110:113], v[194:197], v[58:61]
	v_mfma_f32_16x16x32_bf16 v[54:57], v[102:105], v[210:213], v[54:57]
	v_mfma_f32_16x16x32_bf16 v[46:49], v[110:113], v[210:213], v[46:49]
	v_mfma_f32_16x16x32_bf16 v[30:33], v[102:105], v[218:221], v[30:33]
	v_mfma_f32_16x16x32_bf16 v[26:29], v[110:113], v[218:221], v[26:29]
	v_mfma_f32_16x16x32_bf16 v[22:25], v[102:105], v[226:229], v[22:25]
	v_mfma_f32_16x16x32_bf16 v[14:17], v[110:113], v[226:229], v[14:17]
	s_setprio 0
	s_setprio 1
	v_mfma_f32_16x16x32_bf16 v[50:53], v[174:177], v[190:193], v[50:53]
	v_mfma_f32_16x16x32_bf16 v[42:45], v[182:185], v[190:193], v[42:45]
	v_mfma_f32_16x16x32_bf16 v[38:41], v[174:177], v[198:201], v[38:41]
	v_mfma_f32_16x16x32_bf16 v[34:37], v[182:185], v[198:201], v[34:37]
	v_mfma_f32_16x16x32_bf16 v[18:21], v[174:177], v[214:217], v[18:21]
	v_mfma_f32_16x16x32_bf16 v[10:13], v[182:185], v[214:217], v[10:13]
	v_mfma_f32_16x16x32_bf16 v[6:9], v[174:177], v[222:225], v[6:9]
	v_mfma_f32_16x16x32_bf16 v[2:5], v[182:185], v[222:225], v[2:5]
	v_mfma_f32_16x16x32_bf16 v[50:53], v[178:181], v[194:197], v[50:53]
	v_mfma_f32_16x16x32_bf16 v[42:45], v[186:189], v[194:197], v[42:45]
	v_mfma_f32_16x16x32_bf16 v[38:41], v[178:181], v[210:213], v[38:41]
	v_mfma_f32_16x16x32_bf16 v[34:37], v[186:189], v[210:213], v[34:37]
	v_mfma_f32_16x16x32_bf16 v[18:21], v[178:181], v[218:221], v[18:21]
	v_mfma_f32_16x16x32_bf16 v[10:13], v[186:189], v[218:221], v[10:13]
	v_mfma_f32_16x16x32_bf16 v[6:9], v[178:181], v[226:229], v[6:9]
	v_mfma_f32_16x16x32_bf16 v[2:5], v[186:189], v[226:229], v[2:5]
	s_setprio 0
	s_barrier
	s_add_i32 s11, 0, 0x18000
	s_add_i32 s92, 0, 0x1c000
	v_add_u32_e32 v110, s11, v158
	v_add_u32_e32 v173, s92, v158
	ds_read_b128 v[98:101], v110
	ds_read_b128 v[102:105], v110 offset:1024
	ds_read_b128 v[106:109], v110 offset:2048
	ds_read_b128 v[110:113], v110 offset:3072
	ds_read_b128 v[174:177], v173
	ds_read_b128 v[178:181], v173 offset:1024
	ds_read_b128 v[182:185], v173 offset:2048
	ds_read_b128 v[186:189], v173 offset:3072
	s_add_u32 s88, s88, 0x40000
	s_addc_u32 s89, s89, 0
	s_mov_b32 m0, s70
	v_lshl_add_u64 v[230:231], s[88:89], 0, v[150:151]
	global_load_lds_dwordx4 v[230:231], off
	v_lshl_add_u64 v[230:231], s[88:89], 0, v[148:149]
	s_mov_b32 m0, s71
	s_nop 0
	global_load_lds_dwordx4 v[230:231], off
	ds_read_b128 v[190:193], v172 offset:32768
	ds_read_b128 v[194:197], v172 offset:33792
	ds_read_b128 v[198:201], v172 offset:34816
	ds_read_b128 v[210:213], v172 offset:35840
	ds_read_b128 v[214:217], v172 offset:36864
	ds_read_b128 v[218:221], v172 offset:37888
	ds_read_b128 v[222:225], v172 offset:38912
	ds_read_b128 v[226:229], v172 offset:39936
	s_waitcnt vmcnt(8)
	s_waitcnt lgkmcnt(0)
	s_barrier
	s_setprio 1
	s_waitcnt lgkmcnt(0)
	v_mfma_f32_16x16x32_bf16 v[142:145], v[98:101], v[190:193], v[142:145]
	v_mfma_f32_16x16x32_bf16 v[138:141], v[106:109], v[190:193], v[138:141]
	v_mfma_f32_16x16x32_bf16 v[134:137], v[98:101], v[198:201], v[134:137]
	v_mfma_f32_16x16x32_bf16 v[130:133], v[106:109], v[198:201], v[130:133]
	v_mfma_f32_16x16x32_bf16 v[94:97], v[98:101], v[214:217], v[94:97]
	v_mfma_f32_16x16x32_bf16 v[90:93], v[106:109], v[214:217], v[90:93]
	v_mfma_f32_16x16x32_bf16 v[78:81], v[98:101], v[222:225], v[78:81]
	v_mfma_f32_16x16x32_bf16 v[74:77], v[106:109], v[222:225], v[74:77]
	v_mfma_f32_16x16x32_bf16 v[142:145], v[102:105], v[194:197], v[142:145]
	v_mfma_f32_16x16x32_bf16 v[138:141], v[110:113], v[194:197], v[138:141]
	v_mfma_f32_16x16x32_bf16 v[134:137], v[102:105], v[210:213], v[134:137]
	v_mfma_f32_16x16x32_bf16 v[130:133], v[110:113], v[210:213], v[130:133]
	v_mfma_f32_16x16x32_bf16 v[94:97], v[102:105], v[218:221], v[94:97]
	v_mfma_f32_16x16x32_bf16 v[90:93], v[110:113], v[218:221], v[90:93]
	v_mfma_f32_16x16x32_bf16 v[78:81], v[102:105], v[226:229], v[78:81]
	v_mfma_f32_16x16x32_bf16 v[74:77], v[110:113], v[226:229], v[74:77]
	s_setprio 0
	s_setprio 1
	v_mfma_f32_16x16x32_bf16 v[126:129], v[174:177], v[190:193], v[126:129]
	v_mfma_f32_16x16x32_bf16 v[122:125], v[182:185], v[190:193], v[122:125]
	v_mfma_f32_16x16x32_bf16 v[118:121], v[174:177], v[198:201], v[118:121]
	v_mfma_f32_16x16x32_bf16 v[114:117], v[182:185], v[198:201], v[114:117]
	v_mfma_f32_16x16x32_bf16 v[86:89], v[174:177], v[214:217], v[86:89]
	v_mfma_f32_16x16x32_bf16 v[82:85], v[182:185], v[214:217], v[82:85]
	v_mfma_f32_16x16x32_bf16 v[70:73], v[174:177], v[222:225], v[70:73]
	v_mfma_f32_16x16x32_bf16 v[66:69], v[182:185], v[222:225], v[66:69]
	v_mfma_f32_16x16x32_bf16 v[126:129], v[178:181], v[194:197], v[126:129]
	v_mfma_f32_16x16x32_bf16 v[122:125], v[186:189], v[194:197], v[122:125]
	v_mfma_f32_16x16x32_bf16 v[118:121], v[178:181], v[210:213], v[118:121]
	v_mfma_f32_16x16x32_bf16 v[114:117], v[186:189], v[210:213], v[114:117]
	v_mfma_f32_16x16x32_bf16 v[86:89], v[178:181], v[218:221], v[86:89]
	v_mfma_f32_16x16x32_bf16 v[82:85], v[186:189], v[218:221], v[82:85]
	v_mfma_f32_16x16x32_bf16 v[70:73], v[178:181], v[226:229], v[70:73]
	v_mfma_f32_16x16x32_bf16 v[66:69], v[186:189], v[226:229], v[66:69]
	s_setprio 0
	s_barrier
; #define LAS __attribute__((address_space(3)))
; #define PG8_STAGE(bufoff, gbase, voff) do { _Pragma("unroll") for (int _i = 0; _i < 2; ++_i) \
;         __builtin_amdgcn_global_load_lds((const unsigned*)((const char*)(gbase) + (voff)[_i]), (LAS unsigned*)(lds + (bufoff) + ldsw + _i * 8192), 16, 0, 0); } while (0)
; #define PG8_LDA(dst, b, h) do { _Pragma("unroll") for (int m = 0; m < 4; ++m) _Pragma("unroll") for (int k = 0; k < 2; ++k) dst[m][k] = *(const LAS bf16x8*)(lds + PG8_SA(b, h) + aoff + m * 2048 + k * 1024); } while (0)
; #define PG8_MMA(ai, bj, At, Bt) do { __builtin_amdgcn_s_setprio(1); _Pragma("unroll") for (int m = 0; m < 4; ++m) _Pragma("unroll") for (int n = 0; n < 2; ++n) _Pragma("unroll") for (int k = 0; k < 2; ++k) \
;         acc[ai][bj][m][n] = __builtin_amdgcn_mfma_f32_16x16x32_bf16(Bt[n][k], At[m][k], acc[ai][bj][m][n], 0, 0, 0); __builtin_amdgcn_s_setprio(0); } while (0)
; #define PG8_WAIT_V(n) asm volatile("s_waitcnt vmcnt(" #n ")" ::: "memory")
; #define PG8_BAR __builtin_amdgcn_s_barrier()
; template <class Epi>
; __device__ __forceinline__ void gemm_phase(LAS unsigned char* lds, const int tid, const Gemm g, const StaticOrder& S, const Epi& E) {
;     ...
;             PG8_LDA(At, 1, 1); PG8_STAGE(PG8_SB(1, 0), b3, voffB); PG8_STAGE(PG8_SB(1, 1), b3 + hstepB, voffB); PG8_STAGE(PG8_SA(1, 0), a3, voffA);
;             PG8_WAIT_V(8); PG8_WAIT_L(0); PG8_BAR; PG8_MMA(1, 0, At, B0); PG8_MMA(1, 1, At, B1); PG8_BAR; PG8_SCHED;
;         }
;         if (wr == 0) PG8_BAR;
;     template <int NA, int NM> __device__ __forceinline__ void operator()(const f32x4 (&acc)[NA][2][NM][2], const pg8::Unit& u, int ro, int wr, int wc, int fr, int fq) const {
;         const int j = u.pm < 32 ? 0 : (u.pm < 64 ? 1 : 2);
;         const int colt = u.pn * 256 + wc * 32 + 8 * fq;
;         const LAS float* rsl = EpiCommon::rstd_slot(ssq, u, wr, wc, fr, fq);
;         f32x4 bv[2][2];
; #pragma unroll
;         for (int bj = 0; bj < 2; ++bj)
; #pragma unroll
;             for (int n = 0; n < 2; ++n) bv[bj][n] = *(const f32x4*)(bias + (size_t)j * NUP + colt + bj * 128 + 4 * n);
; #pragma unroll
;         for (int ai = 0; ai < NA; ++ai)
; #pragma unroll
;             for (int m = 0; m < NM; ++m) {
;                 const int row = u.pm * 256 + ro + ai * 128 + wr * 64 + m * 16 + fr;
;                 const float rs = rsl[ro + ai * 128 + m * 16];
; #pragma unroll
	s_add_i32 s11, s11, s28
	v_lshl_add_u64 v[162:163], v[162:163], 0, s[36:37]
	s_mov_b32 m0, s11
	s_nop 0
	global_load_lds_dwordx4 v[162:163], off
	s_add_i32 m0, s11, 0x2000
	s_add_u32 s30, s30, 0x40080
	v_lshl_add_u64 v[162:163], v[164:165], 0, s[36:37]
	s_addc_u32 s31, s31, 0
	s_add_i32 s11, s92, s28
	global_load_lds_dwordx4 v[162:163], off
	v_lshl_add_u64 v[162:163], s[30:31], 0, v[0:1]
	s_mov_b32 m0, s11
	s_nop 0
	global_load_lds_dwordx4 v[162:163], off
	v_lshl_add_u64 v[162:163], s[30:31], 0, v[146:147]
	s_add_i32 m0, s11, 0x2000
	s_nop 0
	global_load_lds_dwordx4 v[162:163], off
	v_lshl_add_u64 v[162:163], v[202:203], 0, s[36:37]
	s_mov_b32 m0, s72
	s_nop 0
	global_load_lds_dwordx4 v[162:163], off
	v_lshl_add_u64 v[162:163], v[206:207], 0, s[36:37]
	s_mov_b32 m0, s73
	s_nop 0
	global_load_lds_dwordx4 v[162:163], off
	ds_read_b128 v[190:193], v172 offset:49152
	ds_read_b128 v[194:197], v172 offset:50176
	ds_read_b128 v[198:201], v172 offset:51200
	ds_read_b128 v[210:213], v172 offset:52224
	ds_read_b128 v[214:217], v172 offset:53248
	ds_read_b128 v[218:221], v172 offset:54272
	ds_read_b128 v[222:225], v172 offset:55296
	ds_read_b128 v[226:229], v172 offset:56320
	s_waitcnt vmcnt(8)
	s_waitcnt lgkmcnt(0)
	s_barrier
	s_setprio 1
	s_waitcnt lgkmcnt(0)
	v_mfma_f32_16x16x32_bf16 v[62:65], v[98:101], v[190:193], v[62:65]
	v_mfma_f32_16x16x32_bf16 v[58:61], v[106:109], v[190:193], v[58:61]
	v_mfma_f32_16x16x32_bf16 v[54:57], v[98:101], v[198:201], v[54:57]
	v_mfma_f32_16x16x32_bf16 v[46:49], v[106:109], v[198:201], v[46:49]
	v_mfma_f32_16x16x32_bf16 v[30:33], v[98:101], v[214:217], v[30:33]
	v_mfma_f32_16x16x32_bf16 v[26:29], v[106:109], v[214:217], v[26:29]
	v_mfma_f32_16x16x32_bf16 v[22:25], v[98:101], v[222:225], v[22:25]
	v_mfma_f32_16x16x32_bf16 v[14:17], v[106:109], v[222:225], v[14:17]
	v_mfma_f32_16x16x32_bf16 v[62:65], v[102:105], v[194:197], v[62:65]
	v_mfma_f32_16x16x32_bf16 v[58:61], v[110:113], v[194:197], v[58:61]
	v_mfma_f32_16x16x32_bf16 v[54:57], v[102:105], v[210:213], v[54:57]
	v_mfma_f32_16x16x32_bf16 v[46:49], v[110:113], v[210:213], v[46:49]
	v_mfma_f32_16x16x32_bf16 v[30:33], v[102:105], v[218:221], v[30:33]
	v_mfma_f32_16x16x32_bf16 v[26:29], v[110:113], v[218:221], v[26:29]
	v_mfma_f32_16x16x32_bf16 v[22:25], v[102:105], v[226:229], v[22:25]
	v_mfma_f32_16x16x32_bf16 v[14:17], v[110:113], v[226:229], v[14:17]
	s_setprio 0
	s_setprio 1
	v_mfma_f32_16x16x32_bf16 v[50:53], v[174:177], v[190:193], v[50:53]
	v_mfma_f32_16x16x32_bf16 v[42:45], v[182:185], v[190:193], v[42:45]
	v_mfma_f32_16x16x32_bf16 v[38:41], v[174:177], v[198:201], v[38:41]
	v_mfma_f32_16x16x32_bf16 v[34:37], v[182:185], v[198:201], v[34:37]
	v_mfma_f32_16x16x32_bf16 v[18:21], v[174:177], v[214:217], v[18:21]
	v_mfma_f32_16x16x32_bf16 v[10:13], v[182:185], v[214:217], v[10:13]
	v_mfma_f32_16x16x32_bf16 v[6:9], v[174:177], v[222:225], v[6:9]
	v_mfma_f32_16x16x32_bf16 v[2:5], v[182:185], v[222:225], v[2:5]
	v_mfma_f32_16x16x32_bf16 v[50:53], v[178:181], v[194:197], v[50:53]
	v_mfma_f32_16x16x32_bf16 v[42:45], v[186:189], v[194:197], v[42:45]
	v_mfma_f32_16x16x32_bf16 v[38:41], v[178:181], v[210:213], v[38:41]
	v_mfma_f32_16x16x32_bf16 v[34:37], v[186:189], v[210:213], v[34:37]
	v_mfma_f32_16x16x32_bf16 v[18:21], v[178:181], v[218:221], v[18:21]
	v_mfma_f32_16x16x32_bf16 v[10:13], v[186:189], v[218:221], v[10:13]
	v_mfma_f32_16x16x32_bf16 v[6:9], v[178:181], v[226:229], v[6:9]
	v_mfma_f32_16x16x32_bf16 v[2:5], v[186:189], v[226:229], v[2:5]
	s_setprio 0
	s_barrier
	s_add_i32 s17, s17, 2
	s_add_u32 s82, s82, 0x100
	s_addc_u32 s83, s83, 0
	s_add_u32 vcc_hi, vcc_hi, 0x100
	s_addc_u32 s27, s27, 0
	s_cmp_gt_u32 s17, 13
	s_cbranch_scc0 .LBB0_1912
	s_and_b64 vcc, exec, s[2:3]
	s_cbranch_vccz .LBB0_1915
	s_and_b64 vcc, exec, s[62:63]
	s_cbranch_vccnz .LBB0_1915
	s_barrier
.LBB0_1915:
	s_cmp_lt_i32 s68, 64
	s_movk_i32 s7, 0x2c00
	s_cselect_b32 s5, 0x1600, s7
	s_cmp_gt_i32 s68, 31
	s_cselect_b32 s5, s5, 0
	s_lshl_b32 s5, s5, 2
	v_lshl_or_b32 v162, s64, 8, v159
	s_add_u32 s30, s16, s5
	s_addc_u32 s31, s26, 0
	v_ashrrev_i32_e32 v163, 31, v162
	v_lshl_add_u64 v[102:103], v[162:163], 2, s[30:31]
	global_load_dwordx4 v[106:109], v[102:103], off offset:16
	global_load_dwordx4 v[110:113], v[102:103], off
	global_load_dwordx4 v[98:101], v[102:103], off offset:528
	s_nop 0
	global_load_dwordx4 v[102:105], v[102:103], off offset:512
	v_lshl_add_u32 v174, s69, 10, v171
	ds_read2_b32 v[164:165], v174 offset1:16
	v_readlane_b32 s30, v254, 19
	s_lshl_b32 s5, s68, 8
	v_readlane_b32 s31, v254, 20
	v_add_u32_e32 v173, s5, v157
	s_andn2_b64 vcc, exec, s[62:63]
	s_waitcnt vmcnt(0) lgkmcnt(0)
; __device__ __forceinline__ unsigned pk2(float lo, float hi) { const f32x2 v = {lo, hi}; const bf16x2_t b = __builtin_convertvector(v, bf16x2_t); return __builtin_bit_cast(unsigned, b); }
;     template <int NA, int NM> __device__ __forceinline__ void operator()(const f32x4 (&acc)[NA][2][NM][2], const pg8::Unit& u, int ro, int wr, int wc, int fr, int fq) const {
;     ...
;         for (int ai = 0; ai < NA; ++ai)
; #pragma unroll
;             for (int m = 0; m < NM; ++m) {
;                 const int row = u.pm * 256 + ro + ai * 128 + wr * 64 + m * 16 + fr;
;                 const float rs = rsl[ro + ai * 128 + m * 16];
; #pragma unroll
;                 for (int bj = 0; bj < 2; ++bj) {
;                     const f32x4 v0 = acc[ai][bj][m][0] * rs + bv[bj][0], v1 = acc[ai][bj][m][1] * rs + bv[bj][1];
;                     u32x4 w; w.x = pk2(v0.x, v0.y); w.y = pk2(v0.z, v0.w); w.z = pk2(v1.x, v1.y); w.w = pk2(v1.z, v1.w);
;                     *(u32x4*)(UV + (size_t)row * NUP + colt + bj * 128) = w;
;                 }
	v_pk_fma_f32 v[138:139], v[138:139], v[164:165], v[106:107] op_sel_hi:[1,0,1]
	v_pk_fma_f32 v[144:145], v[144:145], v[164:165], v[112:113] op_sel_hi:[1,0,1]
	v_pk_fma_f32 v[142:143], v[142:143], v[164:165], v[110:111] op_sel_hi:[1,0,1]
	v_pk_fma_f32 v[140:141], v[140:141], v[164:165], v[108:109] op_sel_hi:[1,0,1]
	v_cvt_pk_bf16_f32 v142, v142, v143
	v_cvt_pk_bf16_f32 v143, v144, v145
	v_cvt_pk_bf16_f32 v144, v138, v139
	v_mov_b64_e32 v[138:139], s[30:31]
	v_cvt_pk_bf16_f32 v145, v140, v141
	v_mad_i64_i32 v[176:177], s[30:31], v173, s7, v[138:139]
	v_lshlrev_b64 v[140:141], 1, v[162:163]
	v_lshl_add_u64 v[162:163], v[176:177], 0, v[140:141]
	global_store_dwordx4 v[162:163], v[142:145], off
	v_pk_fma_f32 v[128:129], v[128:129], v[164:165], v[104:105] op_sel_hi:[1,0,1]
	v_pk_fma_f32 v[126:127], v[126:127], v[164:165], v[102:103] op_sel_hi:[1,0,1]
	v_pk_fma_f32 v[142:143], v[124:125], v[164:165], v[100:101] op_sel_hi:[1,0,1]
	v_pk_fma_f32 v[124:125], v[122:123], v[164:165], v[98:99] op_sel_hi:[1,0,1]
	v_cvt_pk_bf16_f32 v122, v126, v127
	v_cvt_pk_bf16_f32 v123, v128, v129
	v_cvt_pk_bf16_f32 v124, v124, v125
	v_cvt_pk_bf16_f32 v125, v142, v143
	v_add_u32_e32 v127, s5, v160
	v_mov_b32_e32 v126, v165
	global_store_dwordx4 v[162:163], v[122:125], off offset:256
	v_pk_fma_f32 v[128:129], v[132:133], v[126:127], v[108:109] op_sel_hi:[1,0,1]
	v_pk_fma_f32 v[130:131], v[130:131], v[126:127], v[106:107] op_sel_hi:[1,0,1]
	v_pk_fma_f32 v[124:125], v[136:137], v[126:127], v[112:113] op_sel_hi:[1,0,1]
	v_pk_fma_f32 v[122:123], v[134:135], v[126:127], v[110:111] op_sel_hi:[1,0,1]
	v_pk_fma_f32 v[120:121], v[120:121], v[126:127], v[104:105] op_sel_hi:[1,0,1]
	v_cvt_pk_bf16_f32 v122, v122, v123
	v_cvt_pk_bf16_f32 v123, v124, v125
	v_cvt_pk_bf16_f32 v125, v128, v129
	v_mad_i64_i32 v[128:129], s[30:31], v127, s7, v[138:139]
	v_cvt_pk_bf16_f32 v124, v130, v131
	v_lshl_add_u64 v[128:129], v[128:129], 0, v[140:141]
	global_store_dwordx4 v[128:129], v[122:125], off
	v_pk_fma_f32 v[118:119], v[118:119], v[126:127], v[102:103] op_sel_hi:[1,0,1]
	s_nop 0
	v_pk_fma_f32 v[122:123], v[116:117], v[126:127], v[100:101] op_sel_hi:[1,0,1]
	v_pk_fma_f32 v[116:117], v[114:115], v[126:127], v[98:99] op_sel_hi:[1,0,1]
	v_cvt_pk_bf16_f32 v114, v118, v119
	v_cvt_pk_bf16_f32 v115, v120, v121
	v_cvt_pk_bf16_f32 v116, v116, v117
	v_cvt_pk_bf16_f32 v117, v122, v123
	global_store_dwordx4 v[128:129], v[114:117], off offset:256
	ds_read2_b32 v[114:115], v174 offset0:32 offset1:48
	v_add_u32_e32 v118, s5, v161
	s_waitcnt lgkmcnt(0)
	v_pk_fma_f32 v[94:95], v[94:95], v[114:115], v[110:111] op_sel_hi:[1,0,1]
	v_pk_fma_f32 v[96:97], v[96:97], v[114:115], v[112:113] op_sel_hi:[1,0,1]
	v_pk_fma_f32 v[116:117], v[92:93], v[114:115], v[108:109] op_sel_hi:[1,0,1]
	v_pk_fma_f32 v[92:93], v[90:91], v[114:115], v[106:107] op_sel_hi:[1,0,1]
	v_cvt_pk_bf16_f32 v90, v94, v95
	v_mad_i64_i32 v[94:95], s[30:31], v118, s7, v[138:139]
	v_cvt_pk_bf16_f32 v91, v96, v97
	v_cvt_pk_bf16_f32 v92, v92, v93
	v_cvt_pk_bf16_f32 v93, v116, v117
	v_lshl_add_u64 v[94:95], v[94:95], 0, v[140:141]
	global_store_dwordx4 v[94:95], v[90:93], off
	v_pk_fma_f32 v[88:89], v[88:89], v[114:115], v[104:105] op_sel_hi:[1,0,1]
	v_pk_fma_f32 v[86:87], v[86:87], v[114:115], v[102:103] op_sel_hi:[1,0,1]
	v_pk_fma_f32 v[90:91], v[84:85], v[114:115], v[100:101] op_sel_hi:[1,0,1]
	v_pk_fma_f32 v[84:85], v[82:83], v[114:115], v[98:99] op_sel_hi:[1,0,1]
	v_cvt_pk_bf16_f32 v82, v86, v87
	v_cvt_pk_bf16_f32 v83, v88, v89
	v_cvt_pk_bf16_f32 v84, v84, v85
	v_cvt_pk_bf16_f32 v85, v90, v91
	global_store_dwordx4 v[94:95], v[82:85], off offset:256
	s_nop 1
	v_add_u32_e32 v83, s5, v170
	v_mov_b32_e32 v82, v115
	v_pk_fma_f32 v[78:79], v[78:79], v[82:83], v[110:111] op_sel_hi:[1,0,1]
	v_pk_fma_f32 v[80:81], v[80:81], v[82:83], v[112:113] op_sel_hi:[1,0,1]
	v_pk_fma_f32 v[84:85], v[76:77], v[82:83], v[108:109] op_sel_hi:[1,0,1]
	v_pk_fma_f32 v[76:77], v[74:75], v[82:83], v[106:107] op_sel_hi:[1,0,1]
	v_cvt_pk_bf16_f32 v74, v78, v79
	v_mad_i64_i32 v[78:79], s[30:31], v83, s7, v[138:139]
	v_cvt_pk_bf16_f32 v75, v80, v81
	v_cvt_pk_bf16_f32 v76, v76, v77
	v_cvt_pk_bf16_f32 v77, v84, v85
	v_lshl_add_u64 v[78:79], v[78:79], 0, v[140:141]
	global_store_dwordx4 v[78:79], v[74:77], off
	v_pk_fma_f32 v[72:73], v[72:73], v[82:83], v[104:105] op_sel_hi:[1,0,1]
	v_pk_fma_f32 v[70:71], v[70:71], v[82:83], v[102:103] op_sel_hi:[1,0,1]
	v_pk_fma_f32 v[74:75], v[68:69], v[82:83], v[100:101] op_sel_hi:[1,0,1]
	v_pk_fma_f32 v[68:69], v[66:67], v[82:83], v[98:99] op_sel_hi:[1,0,1]
	v_cvt_pk_bf16_f32 v66, v70, v71
	v_cvt_pk_bf16_f32 v67, v72, v73
	v_cvt_pk_bf16_f32 v68, v68, v69
	v_cvt_pk_bf16_f32 v69, v74, v75
	global_store_dwordx4 v[78:79], v[66:69], off offset:256
	ds_read2_b32 v[66:67], v174 offset0:128 offset1:144
	v_add_u32_e32 v70, 0x80, v173
	s_waitcnt lgkmcnt(0)
; __device__ __forceinline__ unsigned pk2(float lo, float hi) { const f32x2 v = {lo, hi}; const bf16x2_t b = __builtin_convertvector(v, bf16x2_t); return __builtin_bit_cast(unsigned, b); }
; #define PG8_BAR __builtin_amdgcn_s_barrier()
; template <class Epi>
; __device__ __forceinline__ void gemm_phase(LAS unsigned char* lds, const int tid, const Gemm g, const StaticOrder& S, const Epi& E) {
;     ...
;         if (!has_next) break;
; #pragma unroll
;         for (int a = 0; a < 2; ++a)
; #pragma unroll
;             for (int b = 0; b < 2; ++b)
; #pragma unroll
;                 for (int m = 0; m < 4; ++m)
; #pragma unroll
;                     for (int n = 0; n < 2; ++n) acc[a][b][m][n] = (f32x4){0.f, 0.f, 0.f, 0.f};
;         cur = nxt; cA = nA; cB = nB; ++ui;
;         if (wr == 1) PG8_BAR;
;     template <int NA, int NM> __device__ __forceinline__ void operator()(const f32x4 (&acc)[NA][2][NM][2], const pg8::Unit& u, int ro, int wr, int wc, int fr, int fq) const {
;     ...
;         for (int ai = 0; ai < NA; ++ai)
; #pragma unroll
;             for (int m = 0; m < NM; ++m) {
;                 const int row = u.pm * 256 + ro + ai * 128 + wr * 64 + m * 16 + fr;
;                 const float rs = rsl[ro + ai * 128 + m * 16];
; #pragma unroll
;                 for (int bj = 0; bj < 2; ++bj) {
;                     const f32x4 v0 = acc[ai][bj][m][0] * rs + bv[bj][0], v1 = acc[ai][bj][m][1] * rs + bv[bj][1];
;                     u32x4 w; w.x = pk2(v0.x, v0.y); w.y = pk2(v0.z, v0.w); w.z = pk2(v1.x, v1.y); w.w = pk2(v1.z, v1.w);
;                     *(u32x4*)(UV + (size_t)row * NUP + colt + bj * 128) = w;
;                 }
	v_pk_fma_f32 v[62:63], v[62:63], v[66:67], v[110:111] op_sel_hi:[1,0,1]
	v_pk_fma_f32 v[64:65], v[64:65], v[66:67], v[112:113] op_sel_hi:[1,0,1]
	v_pk_fma_f32 v[68:69], v[60:61], v[66:67], v[108:109] op_sel_hi:[1,0,1]
	v_pk_fma_f32 v[60:61], v[58:59], v[66:67], v[106:107] op_sel_hi:[1,0,1]
	v_cvt_pk_bf16_f32 v58, v62, v63
	v_mad_i64_i32 v[62:63], s[30:31], v70, s7, v[138:139]
	v_cvt_pk_bf16_f32 v59, v64, v65
	v_cvt_pk_bf16_f32 v60, v60, v61
	v_cvt_pk_bf16_f32 v61, v68, v69
	v_lshl_add_u64 v[62:63], v[62:63], 0, v[140:141]
	global_store_dwordx4 v[62:63], v[58:61], off
	v_pk_fma_f32 v[52:53], v[52:53], v[66:67], v[104:105] op_sel_hi:[1,0,1]
	v_pk_fma_f32 v[50:51], v[50:51], v[66:67], v[102:103] op_sel_hi:[1,0,1]
	v_pk_fma_f32 v[58:59], v[44:45], v[66:67], v[100:101] op_sel_hi:[1,0,1]
	v_pk_fma_f32 v[44:45], v[42:43], v[66:67], v[98:99] op_sel_hi:[1,0,1]
	v_cvt_pk_bf16_f32 v42, v50, v51
	v_cvt_pk_bf16_f32 v43, v52, v53
	v_cvt_pk_bf16_f32 v44, v44, v45
	v_cvt_pk_bf16_f32 v45, v58, v59
	v_add_u32_e32 v51, 0x90, v173
	v_mov_b32_e32 v50, v67
	global_store_dwordx4 v[62:63], v[42:45], off offset:256
	v_pk_fma_f32 v[46:47], v[46:47], v[50:51], v[106:107] op_sel_hi:[1,0,1]
	v_pk_fma_f32 v[48:49], v[48:49], v[50:51], v[108:109] op_sel_hi:[1,0,1]
	v_pk_fma_f32 v[44:45], v[56:57], v[50:51], v[112:113] op_sel_hi:[1,0,1]
	v_pk_fma_f32 v[42:43], v[54:55], v[50:51], v[110:111] op_sel_hi:[1,0,1]
	v_pk_fma_f32 v[40:41], v[40:41], v[50:51], v[104:105] op_sel_hi:[1,0,1]
	v_cvt_pk_bf16_f32 v42, v42, v43
	v_cvt_pk_bf16_f32 v43, v44, v45
	v_cvt_pk_bf16_f32 v44, v46, v47
	v_mad_i64_i32 v[46:47], s[30:31], v51, s7, v[138:139]
	v_cvt_pk_bf16_f32 v45, v48, v49
	v_lshl_add_u64 v[46:47], v[46:47], 0, v[140:141]
	global_store_dwordx4 v[46:47], v[42:45], off
	v_pk_fma_f32 v[38:39], v[38:39], v[50:51], v[102:103] op_sel_hi:[1,0,1]
	s_nop 0
	v_pk_fma_f32 v[42:43], v[36:37], v[50:51], v[100:101] op_sel_hi:[1,0,1]
	v_pk_fma_f32 v[36:37], v[34:35], v[50:51], v[98:99] op_sel_hi:[1,0,1]
	v_cvt_pk_bf16_f32 v34, v38, v39
	v_cvt_pk_bf16_f32 v35, v40, v41
	v_cvt_pk_bf16_f32 v36, v36, v37
	v_cvt_pk_bf16_f32 v37, v42, v43
	global_store_dwordx4 v[46:47], v[34:37], off offset:256
	ds_read2_b32 v[34:35], v174 offset0:160 offset1:176
	v_add_u32_e32 v38, 0xa0, v173
	s_waitcnt lgkmcnt(0)
	v_pk_fma_f32 v[30:31], v[30:31], v[34:35], v[110:111] op_sel_hi:[1,0,1]
	v_pk_fma_f32 v[32:33], v[32:33], v[34:35], v[112:113] op_sel_hi:[1,0,1]
	v_pk_fma_f32 v[36:37], v[28:29], v[34:35], v[108:109] op_sel_hi:[1,0,1]
	v_pk_fma_f32 v[28:29], v[26:27], v[34:35], v[106:107] op_sel_hi:[1,0,1]
	v_cvt_pk_bf16_f32 v26, v30, v31
	v_mad_i64_i32 v[30:31], s[30:31], v38, s7, v[138:139]
	v_cvt_pk_bf16_f32 v27, v32, v33
	v_cvt_pk_bf16_f32 v28, v28, v29
	v_cvt_pk_bf16_f32 v29, v36, v37
	v_lshl_add_u64 v[30:31], v[30:31], 0, v[140:141]
	global_store_dwordx4 v[30:31], v[26:29], off
	v_pk_fma_f32 v[20:21], v[20:21], v[34:35], v[104:105] op_sel_hi:[1,0,1]
	v_pk_fma_f32 v[18:19], v[18:19], v[34:35], v[102:103] op_sel_hi:[1,0,1]
	v_pk_fma_f32 v[26:27], v[12:13], v[34:35], v[100:101] op_sel_hi:[1,0,1]
	v_pk_fma_f32 v[12:13], v[10:11], v[34:35], v[98:99] op_sel_hi:[1,0,1]
	v_cvt_pk_bf16_f32 v10, v18, v19
	v_cvt_pk_bf16_f32 v11, v20, v21
	v_cvt_pk_bf16_f32 v12, v12, v13
	v_cvt_pk_bf16_f32 v13, v26, v27
	v_add_u32_e32 v19, 0xb0, v173
	v_mov_b32_e32 v18, v35
	global_store_dwordx4 v[30:31], v[10:13], off offset:256
	v_pk_fma_f32 v[14:15], v[14:15], v[18:19], v[106:107] op_sel_hi:[1,0,1]
	v_pk_fma_f32 v[16:17], v[16:17], v[18:19], v[108:109] op_sel_hi:[1,0,1]
	v_pk_fma_f32 v[12:13], v[24:25], v[18:19], v[112:113] op_sel_hi:[1,0,1]
	v_pk_fma_f32 v[10:11], v[22:23], v[18:19], v[110:111] op_sel_hi:[1,0,1]
	v_pk_fma_f32 v[8:9], v[8:9], v[18:19], v[104:105] op_sel_hi:[1,0,1]
	v_cvt_pk_bf16_f32 v10, v10, v11
	v_cvt_pk_bf16_f32 v11, v12, v13
	v_cvt_pk_bf16_f32 v12, v14, v15
	v_mad_i64_i32 v[14:15], s[30:31], v19, s7, v[138:139]
	v_cvt_pk_bf16_f32 v13, v16, v17
	v_lshl_add_u64 v[14:15], v[14:15], 0, v[140:141]
	global_store_dwordx4 v[14:15], v[10:13], off
	v_pk_fma_f32 v[6:7], v[6:7], v[18:19], v[102:103] op_sel_hi:[1,0,1]
	s_mov_b64 s[30:31], -1
	v_pk_fma_f32 v[10:11], v[4:5], v[18:19], v[100:101] op_sel_hi:[1,0,1]
	v_pk_fma_f32 v[4:5], v[2:3], v[18:19], v[98:99] op_sel_hi:[1,0,1]
	v_cvt_pk_bf16_f32 v2, v6, v7
	v_cvt_pk_bf16_f32 v3, v8, v9
	v_cvt_pk_bf16_f32 v4, v4, v5
	v_cvt_pk_bf16_f32 v5, v10, v11
	global_store_dwordx4 v[14:15], v[2:5], off offset:256
	s_cbranch_vccnz .LBB0_1904
	s_andn2_b64 vcc, exec, s[0:1]
	s_cbranch_vccnz .LBB0_1903
	s_branch .LBB0_1903
